# static s_setprio 1 for waves 0-3 at kernel entry, no per-segment priority flips in the K-loops (on v24's other edits)
# speedup vs baseline: 1.0101x; 1.0101x over previous
; #define LAS __attribute__((address_space(3)))
; __global__ void __launch_bounds__(NTHREADS, 2) fwd_kernel(Args args) {
;     extern __shared__ __attribute__((aligned(16))) unsigned char lds[];
;     Frame F;
;     F.lds = (LAS unsigned char*)lds; F.tid = threadIdx.x; F.lane = F.tid & 63; F.wave = __builtin_amdgcn_readfirstlane(F.tid >> 6); F.G = gridDim.x; F.ws = args.ws;
_Z10fwd_kernel4Args:
	v_readfirstlane_b32 s100, v0
	s_nop 3
	s_cmp_lt_u32 s100, 0x100
	s_cbranch_scc0 .Lprio_skip
	s_setprio 1
